# attention items handed out dynamically from per-XCD queues (largest first; next item claimed with a device atomic during the current item, broadcast through a spare LDS word)
# baseline (speedup 1.0000x reference)
.LBB0_877:
	s_or_b64 exec, exec, s[0:1]
	v_mov_b32_e32 v1, v254
	s_waitcnt lgkmcnt(0)
	s_barrier
	s_cmp_lg_u32 0, -1
	v_lshrrev_b32_e32 v5, 2, v1
	v_lshrrev_b32_e32 v2, 5, v1
	v_lshlrev_b32_e32 v4, 2, v1
	v_and_b32_e32 v6, 2, v5
	v_and_or_b32 v4, v4, 12, v6
	v_xor_b32_e32 v6, v2, v5
	v_and_or_b32 v4, v6, 1, v4
	v_lshrrev_b32_e32 v6, 1, v1
	v_and_b32_e32 v0, 31, v1
	v_xor_b32_e32 v2, v2, v6
	v_lshlrev_b32_e32 v7, 7, v0
	v_lshlrev_b32_e32 v2, 4, v2
	v_lshlrev_b32_e32 v6, 3, v1
	v_bfe_u32 v3, v1, 5, 1
	v_and_or_b32 v2, v2, 16, v7
	v_and_b32_e32 v7, 0x60, v6
	v_bfe_u32 v8, v1, 2, 2
	v_and_b32_e32 v6, 8, v6
	s_cselect_b32 s0, 0, 0
	v_lshrrev_b32_e32 v9, 3, v1
	v_lshlrev_b32_e32 v12, 10, v3
	v_lshlrev_b32_e32 v13, 8, v8
	v_add_u32_e32 v6, s0, v6
	v_and_b32_e32 v10, 2, v9
	v_bfe_u32 v11, v1, 1, 1
	v_add3_u32 v6, v6, v12, v13
	v_or_b32_e32 v13, 2, v3
	v_lshlrev_b32_e32 v0, 8, v0
	v_bitop3_b32 v12, v10, v3, v11 bitop3:0x36
	v_bitop3_b32 v10, v10, v13, v11 bitop3:0x36
	v_lshl_or_b32 v198, v4, 4, v0
	v_lshlrev_b32_e32 v0, 4, v1
	v_lshlrev_b32_e32 v10, 4, v10
	s_movk_i32 s0, 0x800
	v_lshlrev_b32_e32 v8, 6, v8
	s_movk_i32 s16, 0x4000
	v_and_b32_e32 v0, 0x1f0, v0
	v_lshl_add_u32 v12, v12, 4, v6
	v_add3_u32 v6, v6, v10, s0
	v_xor_b32_e32 v10, 64, v8
	v_or3_b32 v199, v2, v7, s16
	v_lshl_or_b32 v2, v3, 9, v0
	v_mov_b32_e32 v0, 0
	v_add_u32_e32 v188, v12, v8
	v_add_u32_e32 v189, v6, v8
	v_add_u32_e32 v192, v12, v10
	v_add_u32_e32 v193, v6, v10
	v_xor_b32_e32 v10, 0x80, v8
	v_xor_b32_e32 v8, 0xc0, v8
	v_mov_b32_e32 v3, v0
	v_add_u32_e32 v196, v12, v8
	v_add_u32_e32 v197, v6, v8
	v_lshl_add_u64 v[162:163], s[36:37], 0, v[2:3]
	v_and_b32_e32 v2, 15, v1
	v_and_b32_e32 v5, 12, v5
	v_bfe_u32 v8, v1, 6, 2
	v_bitop3_b32 v2, v5, v2, v8 bitop3:0x36
	s_not_b32 s0, s2
	v_add_u32_e32 v3, 0x200, v1
	v_lshrrev_b32_e32 v4, 4, v1
	v_lshlrev_b32_e32 v2, 4, v2
	s_movk_i32 s7, 0x180
	s_add_i32 s17, s30, s0
	v_mad_u64_u32 v[164:165], s[0:1], v4, s7, v[2:3]
	v_bfe_u32 v7, v1, 4, 5
	v_lshrrev_b32_e32 v5, 4, v3
	s_mov_b32 s0, 0x1ffffe0
	v_add_u32_e32 v195, v6, v10
	s_movk_i32 s6, 0xc0
	v_ashrrev_i32_e32 v6, 6, v1
	v_ashrrev_i32_e32 v200, 8, v1
	v_and_or_b32 v5, v5, s0, v7
	v_xor_b32_e32 v1, v4, v1
	v_mad_u64_u32 v[166:167], s[0:1], v5, s7, v[2:3]
	v_mul_lo_u32 v5, v9, s6
	v_lshlrev_b32_e32 v1, 3, v1
	v_and_or_b32 v1, v1, 56, v5
	v_mov_b32_e32 v5, 0x100
	v_lshlrev_b32_e32 v4, 10, v6
	v_lshl_add_u32 v168, v1, 1, v5
	v_lshrrev_b32_e32 v1, 9, v3
	v_mul_u32_u24_e32 v1, 0x3000, v1
	v_mul_u32_u24_e32 v3, 0x180, v7
	v_add_u32_e32 v203, 0, v4
	s_mov_b32 s3, 0
	v_add_u32_e32 v194, v12, v10
	v_and_b32_e32 v201, 3, v6
	v_bfe_u32 v202, v6, 1, 1
	v_mov_b32_e32 v165, v0
	v_mov_b32_e32 v167, v0
	v_mov_b32_e32 v169, v0
	s_movk_i32 s36, 0x3000
	v_add3_u32 v170, v1, v3, v2
	v_mov_b32_e32 v171, v0
	s_movk_i32 s37, 0x1000
	s_movk_i32 s40, 0x2000
	v_add_u32_e32 v204, 0x2000, v203
	v_add_u32_e32 v205, 0x4000, v203
	s_mov_b64 s[0:1], 0x1dc06000
	s_mov_b32 s41, 0x8000
	s_mov_b64 s[6:7], 0x1dc0c000
	s_movk_i32 s44, 0xfe0
	s_movk_i32 s45, 0x2200
	s_mov_b32 s50, 0xc000
	s_mov_b32 s51, 0x10000
	s_mov_b32 s52, 0x14000
	s_mov_b32 s53, 0x18000
	v_mbcnt_hi_u32_b32 v191, -1, v186
	v_readfirstlane_b32 s74, v203
	v_readfirstlane_b32 s76, v254
	s_nop 0
	s_bfe_u32 s76, s76, 0x10007
	s_mov_b32 s77, s2
	s_and_b32 s82, s2, 7
	s_lshl_b32 s82, s82, 6
	s_add_u32 s82, s82, 0x32000
	s_add_u32 s80, s28, s82
	s_addc_u32 s81, s29, 0
	s_mov_b32 s54, 0
	s_branch .LBB0_879

.LBB0_879:
	s_mov_b32 s9, s77
	s_mov_b32 s3, 0
	s_mov_b32 s8, s77
	s_cmpk_gt_i32 s9, 0x7ff
	s_mov_b32 s14, 5
	s_cbranch_scc1 .LBB0_894
	s_cmp_lg_u32 s74, 0
	s_cbranch_scc1 .Latt_noclaim
	s_mov_b64 s[78:79], exec
	s_mov_b64 exec, 1
	v_mov_b32_e32 v244, 1
	global_atomic_add v245, v0, v244, s[80:81] sc0
	s_mov_b64 exec, s[78:79]
.Latt_noclaim:
	s_ashr_i32 s12, s9, 6
	s_and_b32 s15, s9, 7
	s_lshr_b32 s9, s9, 2
	s_sub_i32 s14, 31, s12
	s_and_b32 s9, s9, 14
	v_add_u32_e32 v206, s9, v200
	s_lshl_b32 s9, s15, 12
	s_lshl_b32 s55, s14, 7
	s_add_i32 s55, s55, s9
	s_lshr_b32 s9, s55, 8
	s_and_b32 s9, s9, 0xfffff0
	v_add_u32_e32 v172, s9, v206
	s_lshl_b32 s9, s14, 2
	v_lshlrev_b32_e32 v1, 7, v172
	s_and_b32 s9, s9, 0x7c
	v_or3_b32 v1, v1, s9, v201
	v_mad_i64_i32 v[2:3], s[12:13], v1, s36, v[162:163]
	v_add_co_u32_e32 v4, vcc, s37, v2
	global_load_dwordx4 v[98:101], v[2:3], off
	global_load_dwordx4 v[102:105], v[2:3], off offset:1024
	global_load_dwordx4 v[106:109], v[2:3], off offset:2048
	global_load_dwordx4 v[110:113], v[2:3], off offset:3072
	v_addc_co_u32_e32 v5, vcc, 0, v3, vcc
	v_add_co_u32_e32 v2, vcc, s40, v2
	s_lshl_b32 s56, s14, 1
	s_nop 0
	v_addc_co_u32_e32 v3, vcc, 0, v3, vcc
	global_load_dwordx4 v[114:117], v[4:5], off offset:1024
	global_load_dwordx4 v[118:121], v[4:5], off offset:2048
	global_load_dwordx4 v[122:125], v[2:3], off offset:-4096
	global_load_dwordx4 v[126:129], v[4:5], off offset:3072
	global_load_dwordx4 v[130:133], v[2:3], off
	global_load_dwordx4 v[134:137], v[2:3], off offset:1024
	global_load_dwordx4 v[138:141], v[2:3], off offset:2048
	global_load_dwordx4 v[142:145], v[2:3], off offset:3072
	s_mul_i32 s15, s15, 0x180000
	s_add_u32 s12, s42, s15
	s_addc_u32 s13, s43, 0
	v_readfirstlane_b32 s9, v203
	v_lshl_add_u64 v[2:3], s[12:13], 0, v[164:165]
	s_mov_b32 m0, s9
	v_readfirstlane_b32 s9, v204
	global_load_lds_dwordx4 v[2:3], off
	v_lshl_add_u64 v[2:3], s[12:13], 0, v[166:167]
	s_mov_b32 m0, s9
	v_readfirstlane_b32 s9, v205
	global_load_lds_dwordx4 v[2:3], off
	v_lshl_add_u64 v[2:3], s[12:13], 0, v[168:169]
	s_mov_b32 m0, s9
	s_add_i32 s8, s3, s8
	global_load_lds_dwordx4 v[2:3], off
	s_and_b32 s8, s8, 7
	v_mov_b32_e32 v14, v0
	v_mov_b32_e32 v15, v0
	s_mul_i32 s8, s8, 0x180000
	v_mov_b32_e32 v1, v0
	v_mov_b32_e32 v2, v0
	v_mov_b32_e32 v3, v0
	v_mov_b32_e32 v4, v0
	v_mov_b32_e32 v5, v0
	v_mov_b32_e32 v6, v0
	v_mov_b32_e32 v7, v0
	v_mov_b32_e32 v8, v0
	v_mov_b32_e32 v9, v0
	v_mov_b32_e32 v10, v0
	v_mov_b32_e32 v11, v0
	v_mov_b32_e32 v12, v0
	v_mov_b32_e32 v13, v0
	v_mov_b64_e32 v[64:65], v[14:15]
	v_mov_b64_e32 v[48:49], v[14:15]
	v_mov_b64_e32 v[32:33], v[14:15]
	s_add_u32 s8, s28, s8
	v_mov_b64_e32 v[62:63], v[12:13]
	v_mov_b64_e32 v[60:61], v[10:11]
	v_mov_b64_e32 v[58:59], v[8:9]
	v_mov_b64_e32 v[56:57], v[6:7]
	v_mov_b64_e32 v[54:55], v[4:5]
	v_mov_b64_e32 v[52:53], v[2:3]
	v_mov_b64_e32 v[50:51], v[0:1]
	v_mov_b64_e32 v[46:47], v[12:13]
	v_mov_b64_e32 v[44:45], v[10:11]
	v_mov_b64_e32 v[42:43], v[8:9]
	v_mov_b64_e32 v[40:41], v[6:7]
	v_mov_b64_e32 v[38:39], v[4:5]
	v_mov_b64_e32 v[36:37], v[2:3]
	v_mov_b64_e32 v[34:35], v[0:1]
	v_mov_b64_e32 v[30:31], v[12:13]
	v_mov_b64_e32 v[28:29], v[10:11]
	v_mov_b64_e32 v[26:27], v[8:9]
	v_mov_b64_e32 v[24:25], v[6:7]
	v_mov_b64_e32 v[22:23], v[4:5]
	v_mov_b64_e32 v[20:21], v[2:3]
	v_mov_b64_e32 v[18:19], v[0:1]
	v_mov_b64_e32 v[16:17], v[14:15]
	s_mov_b32 s57, 0
	s_addc_u32 s9, s29, 0
	v_mov_b64_e32 v[210:211], 0
	v_mov_b64_e32 v[212:213], 0
	v_mov_b64_e32 v[214:215], 0
	v_mov_b64_e32 v[216:217], 0
	v_mov_b64_e32 v[218:219], 0
	v_mov_b64_e32 v[220:221], 0
	v_mov_b64_e32 v[222:223], 0
	v_mov_b64_e32 v[224:225], 0
	v_mov_b32_e32 v173, 0
	v_mov_b64_e32 v[14:15], v[12:13]
	v_mov_b64_e32 v[12:13], v[10:11]
	v_mov_b64_e32 v[10:11], v[8:9]
	v_mov_b64_e32 v[8:9], v[6:7]
	v_mov_b64_e32 v[6:7], v[4:5]
	v_mov_b64_e32 v[4:5], v[2:3]
	v_mov_b64_e32 v[2:3], v[0:1]
	s_or_b32 s75, s56, s76
	s_waitcnt vmcnt(0) lgkmcnt(0)
	s_cmp_lg_u32 s74, 0
	s_cbranch_scc1 .Latt_nopub
	v_readfirstlane_b32 s82, v245
	v_mov_b32_e32 v244, 0x23ff8
	s_nop 0
	v_mov_b32_e32 v245, s82
	ds_write_b32 v244, v245
	s_waitcnt lgkmcnt(0)
.Latt_nopub:
	s_barrier
	v_mov_b32_e32 v244, 0x23ff8
	ds_read_b32 v245, v244
	s_waitcnt lgkmcnt(0)
	v_readfirstlane_b32 s83, v245
	s_nop 1
	s_lshl_b32 s83, s83, 3
	s_and_b32 s82, s2, 7
	s_add_u32 s83, s83, s82
	s_add_u32 s83, s83, s30
	s_branch .LBB0_884

.LBB0_897:
	s_mov_b32 s77, s83
	s_add_i32 s54, s54, 1
	s_add_i32 s3, s3, s30
	s_mov_b64 s[8:9], 0
	s_branch .LBB0_878
